# final RMSNorm: gain loads hoisted out of the store loop, per-step vmcnt(0) removed
# speedup vs baseline: 1.0093x; 1.0093x over previous
; __device__ __forceinline__ float rs_from_ss(float ss) { return rsqrtf(ss * (1.0f / DM) + RMS_EPS); }
; __global__ void __launch_bounds__(NWAVES * 64, 2) fwd_megakernel(Args args) {
;     ...
;         for (int m0 = gw * 8; m0 < M; m0 += NGW * 8) {
;             u32x2 w[8][8]; float r[8];
; #pragma unroll
;             for (int q = 0; q < 8; ++q) { const u32x2* xr = (const u32x2*)(HB + (size_t)(m0 + q) * DM) + lane; r[q] = ss[4 * M + m0 + q];
; #pragma unroll
;                 for (int jj = 0; jj < 8; ++jj) w[q][jj] = xr[64 * jj]; }
;             const f32x4* g4 = (const f32x4*)gf + lane;
; #pragma unroll
;             for (int q = 0; q < 8; ++q) { f32x4* orow = (f32x4*)(out + (size_t)(m0 + q) * DM) + lane; const float rq = rs_from_ss(r[q]);
; #pragma unroll
;                 for (int jj = 0; jj < 8; ++jj) { const f32x4 gg = g4[64 * jj]; f32x4 v;
.LBB0_904:
	v_readlane_b32 s0, v250, 52
	s_cmpk_gt_i32 s0, 0x7ff
	s_cbranch_scc1 .LBB0_907
	v_readlane_b32 s4, v250, 0
	v_mov_b32_e32 v171, 0
	v_readlane_b32 s5, v250, 1
	v_readlane_b32 s8, v250, 4
	v_readlane_b32 s9, v250, 5
	s_mov_b64 s[4:5], 0x1000
	s_lshl_b32 s0, s0, 3
	v_lshl_add_u64 v[12:13], s[8:9], 0, v[170:171]
	v_lshl_add_u64 v[14:15], v[12:13], 0, s[4:5]
	s_mov_b64 s[4:5], 0x1400
	s_lshl_b32 s2, s62, 6
	v_lshl_add_u64 v[16:17], v[12:13], 0, s[4:5]
	s_mov_b64 s[4:5], 0x1800
	v_readlane_b32 s6, v250, 2
	v_readlane_b32 s7, v250, 3
	v_lshl_add_u64 v[18:19], v[12:13], 0, s[4:5]
	s_mov_b64 s[4:5], 0x1c00
	s_ashr_i32 s1, s0, 31
	s_ashr_i32 s3, s2, 31
	v_readlane_b32 s10, v250, 6
	v_lshl_add_u64 v[20:21], v[12:13], 0, s[4:5]
	s_lshl_b64 s[4:5], s[0:1], 2
	s_lshl_b64 s[6:7], s[2:3], 2
	s_lshl_b64 s[8:9], s[0:1], 13
	v_readlane_b32 s11, v250, 7
	s_add_u32 s8, s10, s8
	s_addc_u32 s9, s11, s9
	s_lshl_b64 s[10:11], s[0:1], 12
	s_mov_b32 s14, 0x358637bd
	v_lshl_add_u64 v[22:23], s[8:9], 0, v[170:171]
	s_lshl_b64 s[8:9], s[2:3], 13
	v_lshl_or_b32 v24, v168, 3, s10
	v_mov_b32_e32 v25, s11
	s_lshl_b64 s[10:11], s[2:3], 12
	v_mov_b32_e32 v154, 0x40000
	s_mov_b32 s12, 0x3a000000
	v_mov_b64_e32 v[26:27], s[14:15]
	s_mov_b32 s1, 0x800000
	s_movk_i32 s3, 0x1000
	s_movk_i32 s13, 0x2000
	s_movk_i32 s16, 0x3000
	s_movk_i32 s17, 0x4000
	s_movk_i32 s18, 0x5000
	s_movk_i32 s19, 0x6000
	s_movk_i32 s20, 0x7000
	s_mov_b32 s21, 0x8000
	s_mov_b32 s22, 0x9000
	s_mov_b32 s23, 0xa000
	s_mov_b32 s24, 0xb000
	s_mov_b32 s25, 0xc000
	s_mov_b32 s26, 0xd000
	s_mov_b32 s27, 0xe000
	s_mov_b32 s28, 0xf000
	global_load_dwordx4 v[176:179], v[12:13], off
	global_load_dwordx4 v[180:183], v[12:13], off offset:1024
	global_load_dwordx4 v[184:187], v[12:13], off offset:2048
	global_load_dwordx4 v[188:191], v[12:13], off offset:3072
	global_load_dwordx4 v[192:195], v[14:15], off
	global_load_dwordx4 v[196:199], v[16:17], off
	global_load_dwordx4 v[200:203], v[18:19], off
	global_load_dwordx4 v[204:207], v[20:21], off
.LBB0_906:
	v_lshl_add_u64 v[28:29], s[60:61], 0, v[24:25]
	v_add_co_u32_e32 v0, vcc, 0xf800000, v28
	s_add_u32 s14, s60, s4
	s_nop 0
	v_addc_co_u32_e32 v1, vcc, 0, v29, vcc
	s_addc_u32 s15, s61, s5
	v_add_co_u32_e32 v30, vcc, 0xf801000, v28
	s_add_u32 s30, s14, 0x40000
	s_nop 0
	v_addc_co_u32_e32 v31, vcc, 0, v29, vcc
	s_addc_u32 s31, s15, 0
	global_load_dwordx2 v[156:157], v[0:1], off
	global_load_dwordx2 v[152:153], v[0:1], off offset:512
	global_load_dwordx2 v[150:151], v[0:1], off offset:1024
	global_load_dwordx2 v[148:149], v[0:1], off offset:1536
	global_load_dwordx2 v[146:147], v[0:1], off offset:2048
	global_load_dwordx2 v[144:145], v[0:1], off offset:2560
	global_load_dwordx2 v[142:143], v[0:1], off offset:3072
	global_load_dwordx2 v[140:141], v[0:1], off offset:3584
	global_load_dwordx2 v[138:139], v[30:31], off
	global_load_dwordx2 v[136:137], v[30:31], off offset:512
	global_load_dwordx2 v[134:135], v[30:31], off offset:1024
	global_load_dwordx2 v[132:133], v[30:31], off offset:1536
	s_waitcnt lgkmcnt(0)
	global_load_dwordx2 v[130:131], v[30:31], off offset:2048
	global_load_dwordx2 v[128:129], v[30:31], off offset:2560
	global_load_dwordx2 v[124:125], v[30:31], off offset:3072
	global_load_dwordx2 v[120:121], v[30:31], off offset:3584
	global_load_dwordx4 v[0:3], v171, s[30:31] offset:16
	global_load_dwordx4 v[4:7], v154, s[14:15]
	v_add_co_u32_e32 v32, vcc, 0xf802000, v28
	s_add_i32 s0, s0, s2
	s_nop 0
	v_addc_co_u32_e32 v33, vcc, 0, v29, vcc
	v_add_co_u32_e32 v30, vcc, 0xf803000, v28
	global_load_dwordx2 v[126:127], v[32:33], off
	global_load_dwordx2 v[122:123], v[32:33], off offset:512
	global_load_dwordx2 v[118:119], v[32:33], off offset:1024
	global_load_dwordx2 v[116:117], v[32:33], off offset:1536
	global_load_dwordx2 v[114:115], v[32:33], off offset:2048
	global_load_dwordx2 v[112:113], v[32:33], off offset:2560
	global_load_dwordx2 v[110:111], v[32:33], off offset:3072
	global_load_dwordx2 v[108:109], v[32:33], off offset:3584
	v_addc_co_u32_e32 v31, vcc, 0, v29, vcc
	v_add_co_u32_e32 v32, vcc, 0xf804000, v28
	global_load_dwordx2 v[106:107], v[30:31], off
	global_load_dwordx2 v[104:105], v[30:31], off offset:512
	global_load_dwordx2 v[102:103], v[30:31], off offset:1024
	global_load_dwordx2 v[100:101], v[30:31], off offset:1536
	global_load_dwordx2 v[98:99], v[30:31], off offset:2048
	global_load_dwordx2 v[96:97], v[30:31], off offset:2560
	global_load_dwordx2 v[94:95], v[30:31], off offset:3072
	global_load_dwordx2 v[92:93], v[30:31], off offset:3584
	v_addc_co_u32_e32 v33, vcc, 0, v29, vcc
	v_add_co_u32_e32 v30, vcc, 0xf805000, v28
	global_load_dwordx2 v[90:91], v[32:33], off
	global_load_dwordx2 v[88:89], v[32:33], off offset:512
	global_load_dwordx2 v[86:87], v[32:33], off offset:1024
	global_load_dwordx2 v[84:85], v[32:33], off offset:1536
	global_load_dwordx2 v[82:83], v[32:33], off offset:2048
	global_load_dwordx2 v[80:81], v[32:33], off offset:2560
	global_load_dwordx2 v[78:79], v[32:33], off offset:3072
	global_load_dwordx2 v[76:77], v[32:33], off offset:3584
	v_addc_co_u32_e32 v31, vcc, 0, v29, vcc
	v_add_co_u32_e32 v32, vcc, 0xf806000, v28
	global_load_dwordx2 v[74:75], v[30:31], off
	global_load_dwordx2 v[72:73], v[30:31], off offset:512
	global_load_dwordx2 v[70:71], v[30:31], off offset:1024
	global_load_dwordx2 v[68:69], v[30:31], off offset:1536
	global_load_dwordx2 v[66:67], v[30:31], off offset:2048
	global_load_dwordx2 v[64:65], v[30:31], off offset:2560
	global_load_dwordx2 v[62:63], v[30:31], off offset:3072
	global_load_dwordx2 v[60:61], v[30:31], off offset:3584
	v_addc_co_u32_e32 v33, vcc, 0, v29, vcc
	v_add_co_u32_e32 v28, vcc, 0xf807000, v28
	global_load_dwordx2 v[58:59], v[32:33], off
	global_load_dwordx2 v[56:57], v[32:33], off offset:512
	global_load_dwordx2 v[54:55], v[32:33], off offset:1024
	global_load_dwordx2 v[52:53], v[32:33], off offset:1536
	global_load_dwordx2 v[50:51], v[32:33], off offset:2048
	global_load_dwordx2 v[48:49], v[32:33], off offset:2560
	global_load_dwordx2 v[46:47], v[32:33], off offset:3072
	global_load_dwordx2 v[44:45], v[32:33], off offset:3584
	v_addc_co_u32_e32 v29, vcc, 0, v29, vcc
	global_load_dwordx2 v[42:43], v[28:29], off
	global_load_dwordx2 v[40:41], v[28:29], off offset:512
	global_load_dwordx2 v[38:39], v[28:29], off offset:1024
	global_load_dwordx2 v[36:37], v[28:29], off offset:1536
	global_load_dwordx2 v[34:35], v[28:29], off offset:2048
	global_load_dwordx2 v[32:33], v[28:29], off offset:2560
	global_load_dwordx2 v[30:31], v[28:29], off offset:3072
	s_nop 0
	global_load_dwordx2 v[28:29], v[28:29], off offset:3584
	s_add_u32 s4, s4, s6
	s_addc_u32 s5, s5, s7
	v_lshl_add_u64 v[24:25], v[24:25], 0, s[10:11]
	s_cmpk_gt_i32 s0, 0x3fff
	s_waitcnt vmcnt(0)
; __device__ __forceinline__ float rs_from_ss(float ss) { return rsqrtf(ss * (1.0f / DM) + RMS_EPS); }
; __global__ void __launch_bounds__(NWAVES * 64, 2) fwd_megakernel(Args args) {
;     ...
;             for (int q = 0; q < 8; ++q) { f32x4* orow = (f32x4*)(out + (size_t)(m0 + q) * DM) + lane; const float rq = rs_from_ss(r[q]);
; #pragma unroll
;                 for (int jj = 0; jj < 8; ++jj) { const f32x4 gg = g4[64 * jj]; f32x4 v;
;                     v[0] = __uint_as_float(w[q][jj].x << 16); v[1] = __uint_as_float(w[q][jj].x & 0xffff0000u); v[2] = __uint_as_float(w[q][jj].y << 16); v[3] = __uint_as_float(w[q][jj].y & 0xffff0000u);
;                     orow[64 * jj] = v * rq * gg; } }
	v_lshlrev_b32_e32 v158, 16, v156
	v_and_b32_e32 v159, 0xffff0000, v156
	v_lshlrev_b32_e32 v156, 16, v157
	v_and_b32_e32 v157, 0xffff0000, v157
	v_pk_fma_f32 v[0:1], v[0:1], s[12:13], v[26:27] op_sel_hi:[1,0,0]
	v_pk_fma_f32 v[4:5], v[4:5], s[12:13], v[26:27] op_sel_hi:[1,0,0]
	s_nop 0
	v_mul_f32_e32 v155, 0x4b800000, v4
	v_cmp_gt_f32_e32 vcc, s1, v4
	s_nop 1
	v_cndmask_b32_e32 v4, v4, v155, vcc
	v_rsq_f32_e32 v4, v4
	s_nop 0
	v_mul_f32_e32 v155, 0x45800000, v4
	v_cndmask_b32_e32 v4, v4, v155, vcc
	v_pk_mul_f32 v[158:159], v[4:5], v[158:159] op_sel_hi:[0,1]
	v_pk_mul_f32 v[156:157], v[4:5], v[156:157] op_sel_hi:[0,1]
	v_pk_mul_f32 v[10:11], v[178:179], v[156:157]
	v_pk_mul_f32 v[8:9], v[176:177], v[158:159]
	global_store_dwordx4 v[22:23], v[8:11], off
	v_lshlrev_b32_e32 v156, 16, v152
	v_and_b32_e32 v157, 0xffff0000, v152
	v_lshlrev_b32_e32 v152, 16, v153
	v_and_b32_e32 v153, 0xffff0000, v153
	v_pk_mul_f32 v[152:153], v[4:5], v[152:153] op_sel_hi:[0,1]
	v_pk_mul_f32 v[156:157], v[4:5], v[156:157] op_sel_hi:[0,1]
	v_pk_mul_f32 v[8:9], v[180:181], v[156:157]
	v_pk_mul_f32 v[10:11], v[182:183], v[152:153]
	global_store_dwordx4 v[22:23], v[8:11], off offset:1024
	v_lshlrev_b32_e32 v152, 16, v150
	v_and_b32_e32 v153, 0xffff0000, v150
	v_lshlrev_b32_e32 v150, 16, v151
	v_and_b32_e32 v151, 0xffff0000, v151
	v_pk_mul_f32 v[150:151], v[4:5], v[150:151] op_sel_hi:[0,1]
	v_pk_mul_f32 v[152:153], v[4:5], v[152:153] op_sel_hi:[0,1]
	v_pk_mul_f32 v[8:9], v[184:185], v[152:153]
	v_pk_mul_f32 v[10:11], v[186:187], v[150:151]
	global_store_dwordx4 v[22:23], v[8:11], off offset:2048
	v_lshlrev_b32_e32 v150, 16, v148
	v_and_b32_e32 v151, 0xffff0000, v148
	v_lshlrev_b32_e32 v148, 16, v149
	v_and_b32_e32 v149, 0xffff0000, v149
	v_pk_mul_f32 v[148:149], v[4:5], v[148:149] op_sel_hi:[0,1]
	v_pk_mul_f32 v[150:151], v[4:5], v[150:151] op_sel_hi:[0,1]
	v_pk_mul_f32 v[8:9], v[188:189], v[150:151]
	v_pk_mul_f32 v[10:11], v[190:191], v[148:149]
	global_store_dwordx4 v[22:23], v[8:11], off offset:3072
	v_lshlrev_b32_e32 v150, 16, v146
	v_and_b32_e32 v151, 0xffff0000, v146
	v_lshlrev_b32_e32 v146, 16, v147
	v_and_b32_e32 v147, 0xffff0000, v147
	v_add_co_u32_e32 v148, vcc, s13, v22
	v_pk_mul_f32 v[146:147], v[4:5], v[146:147] op_sel_hi:[0,1]
	v_pk_mul_f32 v[150:151], v[4:5], v[150:151] op_sel_hi:[0,1]
	v_addc_co_u32_e32 v149, vcc, 0, v23, vcc
	v_pk_mul_f32 v[8:9], v[192:193], v[150:151]
	v_pk_mul_f32 v[10:11], v[194:195], v[146:147]
	global_store_dwordx4 v[148:149], v[8:11], off offset:-4096
	v_lshlrev_b32_e32 v150, 16, v144
	v_and_b32_e32 v151, 0xffff0000, v144
	v_lshlrev_b32_e32 v144, 16, v145
	v_and_b32_e32 v145, 0xffff0000, v145
	v_add_co_u32_e32 v146, vcc, s3, v22
	v_pk_mul_f32 v[144:145], v[4:5], v[144:145] op_sel_hi:[0,1]
	v_pk_mul_f32 v[150:151], v[4:5], v[150:151] op_sel_hi:[0,1]
	v_addc_co_u32_e32 v147, vcc, 0, v23, vcc
	v_cmp_gt_f32_e32 vcc, s1, v5
	v_pk_mul_f32 v[8:9], v[196:197], v[150:151]
	v_pk_mul_f32 v[10:11], v[198:199], v[144:145]
	global_store_dwordx4 v[146:147], v[8:11], off offset:1024
	v_lshlrev_b32_e32 v144, 16, v142
	v_and_b32_e32 v145, 0xffff0000, v142
	v_lshlrev_b32_e32 v142, 16, v143
	v_and_b32_e32 v143, 0xffff0000, v143
	v_pk_mul_f32 v[142:143], v[4:5], v[142:143] op_sel_hi:[0,1]
	v_pk_mul_f32 v[144:145], v[4:5], v[144:145] op_sel_hi:[0,1]
	v_pk_mul_f32 v[8:9], v[200:201], v[144:145]
	v_pk_mul_f32 v[10:11], v[202:203], v[142:143]
	global_store_dwordx4 v[146:147], v[8:11], off offset:2048
	v_lshlrev_b32_e32 v142, 16, v140
	v_and_b32_e32 v143, 0xffff0000, v140
	v_lshlrev_b32_e32 v140, 16, v141
	v_and_b32_e32 v141, 0xffff0000, v141
	v_pk_mul_f32 v[140:141], v[4:5], v[140:141] op_sel_hi:[0,1]
	v_pk_mul_f32 v[142:143], v[4:5], v[142:143] op_sel_hi:[0,1]
	v_mul_f32_e32 v4, 0x4b800000, v5
	v_cndmask_b32_e32 v4, v5, v4, vcc
	v_rsq_f32_e32 v4, v4
	v_pk_mul_f32 v[8:9], v[204:205], v[142:143]
	v_pk_mul_f32 v[10:11], v[206:207], v[140:141]
	global_store_dwordx4 v[146:147], v[8:11], off offset:3072
	v_mul_f32_e32 v5, 0x45800000, v4
	v_lshlrev_b32_e32 v140, 16, v138
	v_and_b32_e32 v141, 0xffff0000, v138
	v_lshlrev_b32_e32 v138, 16, v139
	v_and_b32_e32 v139, 0xffff0000, v139
	v_cndmask_b32_e32 v4, v4, v5, vcc
	v_pk_mul_f32 v[138:139], v[4:5], v[138:139] op_sel_hi:[0,1]
	v_pk_mul_f32 v[140:141], v[4:5], v[140:141] op_sel_hi:[0,1]
	v_pk_mul_f32 v[8:9], v[176:177], v[140:141]
	v_pk_mul_f32 v[10:11], v[178:179], v[138:139]
	global_store_dwordx4 v[148:149], v[8:11], off
	v_lshlrev_b32_e32 v138, 16, v136
	v_and_b32_e32 v139, 0xffff0000, v136
	v_lshlrev_b32_e32 v136, 16, v137
	v_and_b32_e32 v137, 0xffff0000, v137
	v_pk_mul_f32 v[136:137], v[4:5], v[136:137] op_sel_hi:[0,1]
	v_pk_mul_f32 v[138:139], v[4:5], v[138:139] op_sel_hi:[0,1]
	v_pk_mul_f32 v[8:9], v[180:181], v[138:139]
	v_pk_mul_f32 v[10:11], v[182:183], v[136:137]
	global_store_dwordx4 v[148:149], v[8:11], off offset:1024
	v_lshlrev_b32_e32 v136, 16, v134
	v_and_b32_e32 v137, 0xffff0000, v134
	v_lshlrev_b32_e32 v134, 16, v135
	v_and_b32_e32 v135, 0xffff0000, v135
	v_pk_mul_f32 v[134:135], v[4:5], v[134:135] op_sel_hi:[0,1]
	v_pk_mul_f32 v[136:137], v[4:5], v[136:137] op_sel_hi:[0,1]
	v_pk_mul_f32 v[8:9], v[184:185], v[136:137]
	v_pk_mul_f32 v[10:11], v[186:187], v[134:135]
	global_store_dwordx4 v[148:149], v[8:11], off offset:2048
	v_lshlrev_b32_e32 v134, 16, v132
	v_and_b32_e32 v135, 0xffff0000, v132
	v_lshlrev_b32_e32 v132, 16, v133
	v_and_b32_e32 v133, 0xffff0000, v133
	v_pk_mul_f32 v[132:133], v[4:5], v[132:133] op_sel_hi:[0,1]
	v_pk_mul_f32 v[134:135], v[4:5], v[134:135] op_sel_hi:[0,1]
	v_pk_mul_f32 v[8:9], v[188:189], v[134:135]
	v_pk_mul_f32 v[10:11], v[190:191], v[132:133]
; __device__ __forceinline__ float rs_from_ss(float ss) { return rsqrtf(ss * (1.0f / DM) + RMS_EPS); }
; __global__ void __launch_bounds__(NWAVES * 64, 2) fwd_megakernel(Args args) {
;     ...
;             const f32x4* g4 = (const f32x4*)gf + lane;
; #pragma unroll
;             for (int q = 0; q < 8; ++q) { f32x4* orow = (f32x4*)(out + (size_t)(m0 + q) * DM) + lane; const float rq = rs_from_ss(r[q]);
; #pragma unroll
;                 for (int jj = 0; jj < 8; ++jj) { const f32x4 gg = g4[64 * jj]; f32x4 v;
;                     v[0] = __uint_as_float(w[q][jj].x << 16); v[1] = __uint_as_float(w[q][jj].x & 0xffff0000u); v[2] = __uint_as_float(w[q][jj].y << 16); v[3] = __uint_as_float(w[q][jj].y & 0xffff0000u);
;                     orow[64 * jj] = v * rq * gg; } }
	global_store_dwordx4 v[148:149], v[8:11], off offset:3072
	v_lshlrev_b32_e32 v134, 16, v130
	v_and_b32_e32 v135, 0xffff0000, v130
	v_lshlrev_b32_e32 v130, 16, v131
	v_and_b32_e32 v131, 0xffff0000, v131
	v_add_co_u32_e32 v132, vcc, s17, v22
	v_pk_mul_f32 v[130:131], v[4:5], v[130:131] op_sel_hi:[0,1]
	v_pk_mul_f32 v[134:135], v[4:5], v[134:135] op_sel_hi:[0,1]
	v_addc_co_u32_e32 v133, vcc, 0, v23, vcc
	v_pk_mul_f32 v[8:9], v[192:193], v[134:135]
	v_pk_mul_f32 v[10:11], v[194:195], v[130:131]
	global_store_dwordx4 v[132:133], v[8:11], off offset:-4096
	v_lshlrev_b32_e32 v134, 16, v128
	v_and_b32_e32 v135, 0xffff0000, v128
	v_lshlrev_b32_e32 v128, 16, v129
	v_and_b32_e32 v129, 0xffff0000, v129
	v_add_co_u32_e32 v130, vcc, s16, v22
	v_pk_mul_f32 v[128:129], v[4:5], v[128:129] op_sel_hi:[0,1]
	v_pk_mul_f32 v[134:135], v[4:5], v[134:135] op_sel_hi:[0,1]
	v_addc_co_u32_e32 v131, vcc, 0, v23, vcc
	v_pk_mul_f32 v[8:9], v[196:197], v[134:135]
	v_pk_mul_f32 v[10:11], v[198:199], v[128:129]
	global_store_dwordx4 v[130:131], v[8:11], off offset:1024
	v_lshlrev_b32_e32 v128, 16, v124
	v_and_b32_e32 v129, 0xffff0000, v124
	v_lshlrev_b32_e32 v124, 16, v125
	v_and_b32_e32 v125, 0xffff0000, v125
	v_pk_mul_f32 v[124:125], v[4:5], v[124:125] op_sel_hi:[0,1]
	v_pk_mul_f32 v[128:129], v[4:5], v[128:129] op_sel_hi:[0,1]
	v_pk_mul_f32 v[8:9], v[200:201], v[128:129]
	v_pk_mul_f32 v[10:11], v[202:203], v[124:125]
	global_store_dwordx4 v[130:131], v[8:11], off offset:2048
	v_lshlrev_b32_e32 v124, 16, v120
	v_and_b32_e32 v125, 0xffff0000, v120
	v_lshlrev_b32_e32 v120, 16, v121
	v_and_b32_e32 v121, 0xffff0000, v121
	v_pk_mul_f32 v[120:121], v[4:5], v[120:121] op_sel_hi:[0,1]
	v_pk_mul_f32 v[4:5], v[4:5], v[124:125] op_sel_hi:[0,1]
	v_pk_mul_f32 v[8:9], v[204:205], v[4:5]
	v_pk_mul_f32 v[10:11], v[206:207], v[120:121]
	global_store_dwordx4 v[130:131], v[8:11], off offset:3072
	v_pk_fma_f32 v[120:121], v[6:7], s[12:13], v[26:27] op_sel_hi:[1,0,0]
	v_lshlrev_b32_e32 v4, 16, v126
	v_mul_f32_e32 v124, 0x4b800000, v120
	v_cmp_gt_f32_e32 vcc, s1, v120
	v_and_b32_e32 v5, 0xffff0000, v126
	v_lshlrev_b32_e32 v6, 16, v127
	v_cndmask_b32_e32 v120, v120, v124, vcc
	v_rsq_f32_e32 v120, v120
	v_and_b32_e32 v7, 0xffff0000, v127
	v_mul_f32_e32 v124, 0x45800000, v120
	v_cndmask_b32_e32 v120, v120, v124, vcc
	v_pk_mul_f32 v[6:7], v[120:121], v[6:7] op_sel_hi:[0,1]
	v_pk_mul_f32 v[4:5], v[120:121], v[4:5] op_sel_hi:[0,1]
	v_pk_mul_f32 v[4:5], v[176:177], v[4:5]
	v_pk_mul_f32 v[6:7], v[178:179], v[6:7]
	global_store_dwordx4 v[132:133], v[4:7], off
	v_lshlrev_b32_e32 v8, 16, v122
	v_and_b32_e32 v9, 0xffff0000, v122
	v_lshlrev_b32_e32 v10, 16, v123
	v_and_b32_e32 v11, 0xffff0000, v123
	v_pk_mul_f32 v[10:11], v[120:121], v[10:11] op_sel_hi:[0,1]
	v_pk_mul_f32 v[8:9], v[120:121], v[8:9] op_sel_hi:[0,1]
	v_pk_mul_f32 v[4:5], v[180:181], v[8:9]
	v_pk_mul_f32 v[6:7], v[182:183], v[10:11]
	global_store_dwordx4 v[132:133], v[4:7], off offset:1024
	v_lshlrev_b32_e32 v8, 16, v118
	v_and_b32_e32 v9, 0xffff0000, v118
	v_lshlrev_b32_e32 v10, 16, v119
	v_and_b32_e32 v11, 0xffff0000, v119
	v_pk_mul_f32 v[10:11], v[120:121], v[10:11] op_sel_hi:[0,1]
	v_pk_mul_f32 v[8:9], v[120:121], v[8:9] op_sel_hi:[0,1]
	v_pk_mul_f32 v[4:5], v[184:185], v[8:9]
	v_pk_mul_f32 v[6:7], v[186:187], v[10:11]
	global_store_dwordx4 v[132:133], v[4:7], off offset:2048
	v_lshlrev_b32_e32 v8, 16, v116
	v_and_b32_e32 v9, 0xffff0000, v116
	v_lshlrev_b32_e32 v10, 16, v117
	v_and_b32_e32 v11, 0xffff0000, v117
	v_pk_mul_f32 v[10:11], v[120:121], v[10:11] op_sel_hi:[0,1]
	v_pk_mul_f32 v[8:9], v[120:121], v[8:9] op_sel_hi:[0,1]
	v_pk_mul_f32 v[4:5], v[188:189], v[8:9]
	v_pk_mul_f32 v[6:7], v[190:191], v[10:11]
	global_store_dwordx4 v[132:133], v[4:7], off offset:3072
	v_lshlrev_b32_e32 v10, 16, v114
	v_and_b32_e32 v11, 0xffff0000, v114
	v_lshlrev_b32_e32 v114, 16, v115
	v_and_b32_e32 v115, 0xffff0000, v115
	v_add_co_u32_e32 v8, vcc, s19, v22
	v_pk_mul_f32 v[114:115], v[120:121], v[114:115] op_sel_hi:[0,1]
	v_pk_mul_f32 v[10:11], v[120:121], v[10:11] op_sel_hi:[0,1]
	v_addc_co_u32_e32 v9, vcc, 0, v23, vcc
	v_pk_mul_f32 v[4:5], v[192:193], v[10:11]
	v_pk_mul_f32 v[6:7], v[194:195], v[114:115]
	global_store_dwordx4 v[8:9], v[4:7], off offset:-4096
	v_lshlrev_b32_e32 v114, 16, v112
	v_and_b32_e32 v115, 0xffff0000, v112
	v_lshlrev_b32_e32 v112, 16, v113
	v_and_b32_e32 v113, 0xffff0000, v113
	v_add_co_u32_e32 v10, vcc, s18, v22
	v_pk_mul_f32 v[112:113], v[120:121], v[112:113] op_sel_hi:[0,1]
	v_pk_mul_f32 v[114:115], v[120:121], v[114:115] op_sel_hi:[0,1]
	v_addc_co_u32_e32 v11, vcc, 0, v23, vcc
	v_cmp_gt_f32_e32 vcc, s1, v121
	v_pk_mul_f32 v[4:5], v[196:197], v[114:115]
	v_pk_mul_f32 v[6:7], v[198:199], v[112:113]
	global_store_dwordx4 v[10:11], v[4:7], off offset:1024
	v_lshlrev_b32_e32 v112, 16, v110
	v_and_b32_e32 v113, 0xffff0000, v110
	v_lshlrev_b32_e32 v110, 16, v111
	v_and_b32_e32 v111, 0xffff0000, v111
	v_pk_mul_f32 v[110:111], v[120:121], v[110:111] op_sel_hi:[0,1]
	v_pk_mul_f32 v[112:113], v[120:121], v[112:113] op_sel_hi:[0,1]
	v_pk_mul_f32 v[4:5], v[200:201], v[112:113]
	v_pk_mul_f32 v[6:7], v[202:203], v[110:111]
	global_store_dwordx4 v[10:11], v[4:7], off offset:2048
	v_lshlrev_b32_e32 v110, 16, v108
	v_and_b32_e32 v111, 0xffff0000, v108
	v_lshlrev_b32_e32 v108, 16, v109
	v_and_b32_e32 v109, 0xffff0000, v109
	v_pk_mul_f32 v[108:109], v[120:121], v[108:109] op_sel_hi:[0,1]
	v_pk_mul_f32 v[110:111], v[120:121], v[110:111] op_sel_hi:[0,1]
	v_pk_mul_f32 v[4:5], v[204:205], v[110:111]
	v_pk_mul_f32 v[6:7], v[206:207], v[108:109]
	global_store_dwordx4 v[10:11], v[4:7], off offset:3072
	v_mul_f32_e32 v10, 0x4b800000, v121
; __device__ __forceinline__ float rs_from_ss(float ss) { return rsqrtf(ss * (1.0f / DM) + RMS_EPS); }
; __global__ void __launch_bounds__(NWAVES * 64, 2) fwd_megakernel(Args args) {
;     ...
;             const f32x4* g4 = (const f32x4*)gf + lane;
; #pragma unroll
;             for (int q = 0; q < 8; ++q) { f32x4* orow = (f32x4*)(out + (size_t)(m0 + q) * DM) + lane; const float rq = rs_from_ss(r[q]);
; #pragma unroll
;                 for (int jj = 0; jj < 8; ++jj) { const f32x4 gg = g4[64 * jj]; f32x4 v;
;                     v[0] = __uint_as_float(w[q][jj].x << 16); v[1] = __uint_as_float(w[q][jj].x & 0xffff0000u); v[2] = __uint_as_float(w[q][jj].y << 16); v[3] = __uint_as_float(w[q][jj].y & 0xffff0000u);
;                     orow[64 * jj] = v * rq * gg; } }
	v_cndmask_b32_e32 v108, v121, v10, vcc
	v_rsq_f32_e32 v108, v108
	v_lshlrev_b32_e32 v10, 16, v106
	v_and_b32_e32 v11, 0xffff0000, v106
	v_lshlrev_b32_e32 v106, 16, v107
	v_mul_f32_e32 v109, 0x45800000, v108
	v_and_b32_e32 v107, 0xffff0000, v107
	v_cndmask_b32_e32 v108, v108, v109, vcc
	v_pk_mul_f32 v[106:107], v[108:109], v[106:107] op_sel_hi:[0,1]
	v_pk_mul_f32 v[10:11], v[108:109], v[10:11] op_sel_hi:[0,1]
	v_pk_mul_f32 v[4:5], v[176:177], v[10:11]
	v_pk_mul_f32 v[6:7], v[178:179], v[106:107]
	global_store_dwordx4 v[8:9], v[4:7], off
	v_lshlrev_b32_e32 v10, 16, v104
	v_and_b32_e32 v11, 0xffff0000, v104
	v_lshlrev_b32_e32 v104, 16, v105
	v_and_b32_e32 v105, 0xffff0000, v105
	v_pk_mul_f32 v[104:105], v[108:109], v[104:105] op_sel_hi:[0,1]
	v_pk_mul_f32 v[10:11], v[108:109], v[10:11] op_sel_hi:[0,1]
	v_pk_mul_f32 v[4:5], v[180:181], v[10:11]
	v_pk_mul_f32 v[6:7], v[182:183], v[104:105]
	global_store_dwordx4 v[8:9], v[4:7], off offset:1024
	v_lshlrev_b32_e32 v10, 16, v102
	v_and_b32_e32 v11, 0xffff0000, v102
	v_lshlrev_b32_e32 v102, 16, v103
	v_and_b32_e32 v103, 0xffff0000, v103
	v_pk_mul_f32 v[102:103], v[108:109], v[102:103] op_sel_hi:[0,1]
	v_pk_mul_f32 v[10:11], v[108:109], v[10:11] op_sel_hi:[0,1]
	v_pk_mul_f32 v[4:5], v[184:185], v[10:11]
	v_pk_mul_f32 v[6:7], v[186:187], v[102:103]
	global_store_dwordx4 v[8:9], v[4:7], off offset:2048
	v_lshlrev_b32_e32 v10, 16, v100
	v_and_b32_e32 v11, 0xffff0000, v100
	v_lshlrev_b32_e32 v100, 16, v101
	v_and_b32_e32 v101, 0xffff0000, v101
	v_pk_mul_f32 v[100:101], v[108:109], v[100:101] op_sel_hi:[0,1]
	v_pk_mul_f32 v[10:11], v[108:109], v[10:11] op_sel_hi:[0,1]
	v_pk_mul_f32 v[4:5], v[188:189], v[10:11]
	v_pk_mul_f32 v[6:7], v[190:191], v[100:101]
	global_store_dwordx4 v[8:9], v[4:7], off offset:3072
	v_lshlrev_b32_e32 v10, 16, v98
	v_and_b32_e32 v11, 0xffff0000, v98
	v_lshlrev_b32_e32 v98, 16, v99
	v_and_b32_e32 v99, 0xffff0000, v99
	v_add_co_u32_e32 v8, vcc, s21, v22
	v_pk_mul_f32 v[98:99], v[108:109], v[98:99] op_sel_hi:[0,1]
	v_pk_mul_f32 v[10:11], v[108:109], v[10:11] op_sel_hi:[0,1]
	v_addc_co_u32_e32 v9, vcc, 0, v23, vcc
	v_pk_mul_f32 v[4:5], v[192:193], v[10:11]
	v_pk_mul_f32 v[6:7], v[194:195], v[98:99]
	global_store_dwordx4 v[8:9], v[4:7], off offset:-4096
	v_lshlrev_b32_e32 v98, 16, v96
	v_and_b32_e32 v99, 0xffff0000, v96
	v_lshlrev_b32_e32 v96, 16, v97
	v_and_b32_e32 v97, 0xffff0000, v97
	v_add_co_u32_e32 v10, vcc, s20, v22
	v_pk_mul_f32 v[96:97], v[108:109], v[96:97] op_sel_hi:[0,1]
	v_pk_mul_f32 v[98:99], v[108:109], v[98:99] op_sel_hi:[0,1]
	v_addc_co_u32_e32 v11, vcc, 0, v23, vcc
	v_cmp_gt_f32_e32 vcc, s1, v0
	v_pk_mul_f32 v[4:5], v[196:197], v[98:99]
	v_pk_mul_f32 v[6:7], v[198:199], v[96:97]
	global_store_dwordx4 v[10:11], v[4:7], off offset:1024
	v_lshlrev_b32_e32 v96, 16, v94
	v_and_b32_e32 v97, 0xffff0000, v94
	v_lshlrev_b32_e32 v94, 16, v95
	v_and_b32_e32 v95, 0xffff0000, v95
	v_pk_mul_f32 v[94:95], v[108:109], v[94:95] op_sel_hi:[0,1]
	v_pk_mul_f32 v[96:97], v[108:109], v[96:97] op_sel_hi:[0,1]
	v_pk_mul_f32 v[4:5], v[200:201], v[96:97]
	v_pk_mul_f32 v[6:7], v[202:203], v[94:95]
	global_store_dwordx4 v[10:11], v[4:7], off offset:2048
	v_lshlrev_b32_e32 v94, 16, v92
	v_and_b32_e32 v95, 0xffff0000, v92
	v_lshlrev_b32_e32 v92, 16, v93
	v_and_b32_e32 v93, 0xffff0000, v93
	v_pk_mul_f32 v[92:93], v[108:109], v[92:93] op_sel_hi:[0,1]
	v_pk_mul_f32 v[94:95], v[108:109], v[94:95] op_sel_hi:[0,1]
	v_pk_mul_f32 v[4:5], v[204:205], v[94:95]
	v_pk_mul_f32 v[6:7], v[206:207], v[92:93]
	global_store_dwordx4 v[10:11], v[4:7], off offset:3072
	v_mul_f32_e32 v10, 0x4b800000, v0
	v_cndmask_b32_e32 v0, v0, v10, vcc
	v_rsq_f32_e32 v0, v0
	v_lshlrev_b32_e32 v10, 16, v90
	v_and_b32_e32 v11, 0xffff0000, v90
	v_lshlrev_b32_e32 v90, 16, v91
	v_mul_f32_e32 v92, 0x45800000, v0
	v_and_b32_e32 v91, 0xffff0000, v91
	v_cndmask_b32_e32 v0, v0, v92, vcc
	v_pk_mul_f32 v[90:91], v[0:1], v[90:91] op_sel_hi:[0,1]
	v_pk_mul_f32 v[10:11], v[0:1], v[10:11] op_sel_hi:[0,1]
	v_pk_mul_f32 v[4:5], v[176:177], v[10:11]
	v_pk_mul_f32 v[6:7], v[178:179], v[90:91]
	global_store_dwordx4 v[8:9], v[4:7], off
	v_lshlrev_b32_e32 v10, 16, v88
	v_and_b32_e32 v11, 0xffff0000, v88
	v_lshlrev_b32_e32 v88, 16, v89
	v_and_b32_e32 v89, 0xffff0000, v89
	v_pk_mul_f32 v[88:89], v[0:1], v[88:89] op_sel_hi:[0,1]
	v_pk_mul_f32 v[10:11], v[0:1], v[10:11] op_sel_hi:[0,1]
	v_pk_mul_f32 v[4:5], v[180:181], v[10:11]
	v_pk_mul_f32 v[6:7], v[182:183], v[88:89]
	global_store_dwordx4 v[8:9], v[4:7], off offset:1024
	v_lshlrev_b32_e32 v10, 16, v86
	v_and_b32_e32 v11, 0xffff0000, v86
	v_lshlrev_b32_e32 v86, 16, v87
	v_and_b32_e32 v87, 0xffff0000, v87
	v_pk_mul_f32 v[86:87], v[0:1], v[86:87] op_sel_hi:[0,1]
	v_pk_mul_f32 v[10:11], v[0:1], v[10:11] op_sel_hi:[0,1]
	v_pk_mul_f32 v[4:5], v[184:185], v[10:11]
	v_pk_mul_f32 v[6:7], v[186:187], v[86:87]
	global_store_dwordx4 v[8:9], v[4:7], off offset:2048
	v_lshlrev_b32_e32 v10, 16, v84
	v_and_b32_e32 v11, 0xffff0000, v84
	v_lshlrev_b32_e32 v84, 16, v85
	v_and_b32_e32 v85, 0xffff0000, v85
	v_pk_mul_f32 v[84:85], v[0:1], v[84:85] op_sel_hi:[0,1]
	v_pk_mul_f32 v[10:11], v[0:1], v[10:11] op_sel_hi:[0,1]
	v_pk_mul_f32 v[4:5], v[188:189], v[10:11]
	v_pk_mul_f32 v[6:7], v[190:191], v[84:85]
	global_store_dwordx4 v[8:9], v[4:7], off offset:3072
	v_lshlrev_b32_e32 v10, 16, v82
	v_and_b32_e32 v11, 0xffff0000, v82
	v_lshlrev_b32_e32 v82, 16, v83
	v_and_b32_e32 v83, 0xffff0000, v83
	v_add_co_u32_e32 v8, vcc, s23, v22
	v_pk_mul_f32 v[82:83], v[0:1], v[82:83] op_sel_hi:[0,1]
	v_pk_mul_f32 v[10:11], v[0:1], v[10:11] op_sel_hi:[0,1]
	v_addc_co_u32_e32 v9, vcc, 0, v23, vcc
	v_pk_mul_f32 v[4:5], v[192:193], v[10:11]
; __device__ __forceinline__ float rs_from_ss(float ss) { return rsqrtf(ss * (1.0f / DM) + RMS_EPS); }
; __global__ void __launch_bounds__(NWAVES * 64, 2) fwd_megakernel(Args args) {
;     ...
;             const f32x4* g4 = (const f32x4*)gf + lane;
; #pragma unroll
;             for (int q = 0; q < 8; ++q) { f32x4* orow = (f32x4*)(out + (size_t)(m0 + q) * DM) + lane; const float rq = rs_from_ss(r[q]);
; #pragma unroll
;                 for (int jj = 0; jj < 8; ++jj) { const f32x4 gg = g4[64 * jj]; f32x4 v;
;                     v[0] = __uint_as_float(w[q][jj].x << 16); v[1] = __uint_as_float(w[q][jj].x & 0xffff0000u); v[2] = __uint_as_float(w[q][jj].y << 16); v[3] = __uint_as_float(w[q][jj].y & 0xffff0000u);
;                     orow[64 * jj] = v * rq * gg; } }
	v_pk_mul_f32 v[6:7], v[194:195], v[82:83]
	global_store_dwordx4 v[8:9], v[4:7], off offset:-4096
	v_lshlrev_b32_e32 v82, 16, v80
	v_and_b32_e32 v83, 0xffff0000, v80
	v_lshlrev_b32_e32 v80, 16, v81
	v_and_b32_e32 v81, 0xffff0000, v81
	v_add_co_u32_e32 v10, vcc, s22, v22
	v_pk_mul_f32 v[80:81], v[0:1], v[80:81] op_sel_hi:[0,1]
	v_pk_mul_f32 v[82:83], v[0:1], v[82:83] op_sel_hi:[0,1]
	v_addc_co_u32_e32 v11, vcc, 0, v23, vcc
	v_cmp_gt_f32_e32 vcc, s1, v1
	v_pk_mul_f32 v[4:5], v[196:197], v[82:83]
	v_pk_mul_f32 v[6:7], v[198:199], v[80:81]
	global_store_dwordx4 v[10:11], v[4:7], off offset:1024
	v_lshlrev_b32_e32 v80, 16, v78
	v_and_b32_e32 v81, 0xffff0000, v78
	v_lshlrev_b32_e32 v78, 16, v79
	v_and_b32_e32 v79, 0xffff0000, v79
	v_pk_mul_f32 v[78:79], v[0:1], v[78:79] op_sel_hi:[0,1]
	v_pk_mul_f32 v[80:81], v[0:1], v[80:81] op_sel_hi:[0,1]
	v_pk_mul_f32 v[4:5], v[200:201], v[80:81]
	v_pk_mul_f32 v[6:7], v[202:203], v[78:79]
	global_store_dwordx4 v[10:11], v[4:7], off offset:2048
	v_lshlrev_b32_e32 v78, 16, v76
	v_and_b32_e32 v79, 0xffff0000, v76
	v_lshlrev_b32_e32 v76, 16, v77
	v_and_b32_e32 v77, 0xffff0000, v77
	v_pk_mul_f32 v[76:77], v[0:1], v[76:77] op_sel_hi:[0,1]
	v_pk_mul_f32 v[78:79], v[0:1], v[78:79] op_sel_hi:[0,1]
	v_mul_f32_e32 v0, 0x4b800000, v1
	v_cndmask_b32_e32 v0, v1, v0, vcc
	v_and_b32_e32 v1, 0xffff0000, v74
	v_pk_mul_f32 v[4:5], v[204:205], v[78:79]
	v_pk_mul_f32 v[6:7], v[206:207], v[76:77]
	global_store_dwordx4 v[10:11], v[4:7], off offset:3072
	v_rsq_f32_e32 v76, v0
	v_lshlrev_b32_e32 v0, 16, v74
	v_lshlrev_b32_e32 v10, 16, v75
	v_and_b32_e32 v11, 0xffff0000, v75
	v_mul_f32_e32 v74, 0x45800000, v76
	v_cndmask_b32_e32 v74, v76, v74, vcc
	v_pk_mul_f32 v[10:11], v[74:75], v[10:11] op_sel_hi:[0,1]
	v_pk_mul_f32 v[0:1], v[74:75], v[0:1] op_sel_hi:[0,1]
	v_pk_mul_f32 v[4:5], v[176:177], v[0:1]
	v_pk_mul_f32 v[6:7], v[178:179], v[10:11]
	global_store_dwordx4 v[8:9], v[4:7], off
	v_lshlrev_b32_e32 v0, 16, v72
	v_and_b32_e32 v1, 0xffff0000, v72
	v_lshlrev_b32_e32 v10, 16, v73
	v_and_b32_e32 v11, 0xffff0000, v73
	v_pk_mul_f32 v[10:11], v[74:75], v[10:11] op_sel_hi:[0,1]
	v_pk_mul_f32 v[0:1], v[74:75], v[0:1] op_sel_hi:[0,1]
	v_pk_mul_f32 v[4:5], v[180:181], v[0:1]
	v_pk_mul_f32 v[6:7], v[182:183], v[10:11]
	global_store_dwordx4 v[8:9], v[4:7], off offset:1024
	v_lshlrev_b32_e32 v0, 16, v70
	v_and_b32_e32 v1, 0xffff0000, v70
	v_lshlrev_b32_e32 v10, 16, v71
	v_and_b32_e32 v11, 0xffff0000, v71
	v_pk_mul_f32 v[10:11], v[74:75], v[10:11] op_sel_hi:[0,1]
	v_pk_mul_f32 v[0:1], v[74:75], v[0:1] op_sel_hi:[0,1]
	v_pk_mul_f32 v[4:5], v[184:185], v[0:1]
	v_pk_mul_f32 v[6:7], v[186:187], v[10:11]
	global_store_dwordx4 v[8:9], v[4:7], off offset:2048
	v_lshlrev_b32_e32 v0, 16, v68
	v_and_b32_e32 v1, 0xffff0000, v68
	v_lshlrev_b32_e32 v10, 16, v69
	v_and_b32_e32 v11, 0xffff0000, v69
	v_pk_mul_f32 v[10:11], v[74:75], v[10:11] op_sel_hi:[0,1]
	v_pk_mul_f32 v[0:1], v[74:75], v[0:1] op_sel_hi:[0,1]
	v_pk_mul_f32 v[4:5], v[188:189], v[0:1]
	v_pk_mul_f32 v[6:7], v[190:191], v[10:11]
	global_store_dwordx4 v[8:9], v[4:7], off offset:3072
	v_lshlrev_b32_e32 v0, 16, v66
	v_and_b32_e32 v1, 0xffff0000, v66
	v_lshlrev_b32_e32 v10, 16, v67
	v_and_b32_e32 v11, 0xffff0000, v67
	v_add_co_u32_e32 v8, vcc, s25, v22
	v_pk_mul_f32 v[10:11], v[74:75], v[10:11] op_sel_hi:[0,1]
	v_pk_mul_f32 v[0:1], v[74:75], v[0:1] op_sel_hi:[0,1]
	v_addc_co_u32_e32 v9, vcc, 0, v23, vcc
	v_pk_mul_f32 v[4:5], v[192:193], v[0:1]
	v_pk_mul_f32 v[6:7], v[194:195], v[10:11]
	global_store_dwordx4 v[8:9], v[4:7], off offset:-4096
	v_lshlrev_b32_e32 v10, 16, v64
	v_and_b32_e32 v11, 0xffff0000, v64
	v_lshlrev_b32_e32 v64, 16, v65
	v_and_b32_e32 v65, 0xffff0000, v65
	v_add_co_u32_e32 v0, vcc, s24, v22
	v_pk_mul_f32 v[64:65], v[74:75], v[64:65] op_sel_hi:[0,1]
	v_pk_mul_f32 v[10:11], v[74:75], v[10:11] op_sel_hi:[0,1]
	v_addc_co_u32_e32 v1, vcc, 0, v23, vcc
	v_pk_mul_f32 v[4:5], v[196:197], v[10:11]
	v_pk_mul_f32 v[6:7], v[198:199], v[64:65]
	global_store_dwordx4 v[0:1], v[4:7], off offset:1024
	v_lshlrev_b32_e32 v10, 16, v62
	v_and_b32_e32 v11, 0xffff0000, v62
	v_lshlrev_b32_e32 v62, 16, v63
	v_and_b32_e32 v63, 0xffff0000, v63
	v_pk_mul_f32 v[62:63], v[74:75], v[62:63] op_sel_hi:[0,1]
	v_pk_mul_f32 v[10:11], v[74:75], v[10:11] op_sel_hi:[0,1]
	v_pk_mul_f32 v[4:5], v[200:201], v[10:11]
	v_pk_mul_f32 v[6:7], v[202:203], v[62:63]
	global_store_dwordx4 v[0:1], v[4:7], off offset:2048
	v_lshlrev_b32_e32 v10, 16, v60
	v_and_b32_e32 v11, 0xffff0000, v60
	v_lshlrev_b32_e32 v60, 16, v61
	v_and_b32_e32 v61, 0xffff0000, v61
	v_pk_mul_f32 v[60:61], v[74:75], v[60:61] op_sel_hi:[0,1]
	v_pk_mul_f32 v[10:11], v[74:75], v[10:11] op_sel_hi:[0,1]
	v_pk_mul_f32 v[4:5], v[204:205], v[10:11]
	v_pk_mul_f32 v[6:7], v[206:207], v[60:61]
	global_store_dwordx4 v[0:1], v[4:7], off offset:3072
	v_pk_fma_f32 v[10:11], v[2:3], s[12:13], v[26:27] op_sel_hi:[1,0,0]
	v_and_b32_e32 v1, 0xffff0000, v58
	v_mul_f32_e32 v0, 0x4b800000, v10
	v_cmp_gt_f32_e32 vcc, s1, v10
	v_lshlrev_b32_e32 v2, 16, v59
	v_and_b32_e32 v3, 0xffff0000, v59
	v_cndmask_b32_e32 v0, v10, v0, vcc
	v_rsq_f32_e32 v10, v0
	v_lshlrev_b32_e32 v0, 16, v58
	v_mul_f32_e32 v58, 0x45800000, v10
	v_cndmask_b32_e32 v10, v10, v58, vcc
	v_pk_mul_f32 v[2:3], v[10:11], v[2:3] op_sel_hi:[0,1]
	v_pk_mul_f32 v[0:1], v[10:11], v[0:1] op_sel_hi:[0,1]
	v_pk_mul_f32 v[0:1], v[176:177], v[0:1]
	v_pk_mul_f32 v[2:3], v[178:179], v[2:3]
	global_store_dwordx4 v[8:9], v[0:3], off
	v_lshlrev_b32_e32 v4, 16, v56
	v_and_b32_e32 v5, 0xffff0000, v56
	v_lshlrev_b32_e32 v6, 16, v57
	v_and_b32_e32 v7, 0xffff0000, v57
	v_pk_mul_f32 v[6:7], v[10:11], v[6:7] op_sel_hi:[0,1]
; __device__ __forceinline__ float rs_from_ss(float ss) { return rsqrtf(ss * (1.0f / DM) + RMS_EPS); }
; __global__ void __launch_bounds__(NWAVES * 64, 2) fwd_megakernel(Args args) {
;     ...
;         for (int m0 = gw * 8; m0 < M; m0 += NGW * 8) {
;             u32x2 w[8][8]; float r[8];
; #pragma unroll
;             for (int q = 0; q < 8; ++q) { const u32x2* xr = (const u32x2*)(HB + (size_t)(m0 + q) * DM) + lane; r[q] = ss[4 * M + m0 + q];
; #pragma unroll
;                 for (int jj = 0; jj < 8; ++jj) w[q][jj] = xr[64 * jj]; }
;             const f32x4* g4 = (const f32x4*)gf + lane;
; #pragma unroll
;             for (int q = 0; q < 8; ++q) { f32x4* orow = (f32x4*)(out + (size_t)(m0 + q) * DM) + lane; const float rq = rs_from_ss(r[q]);
; #pragma unroll
;                 for (int jj = 0; jj < 8; ++jj) { const f32x4 gg = g4[64 * jj]; f32x4 v;
;                     v[0] = __uint_as_float(w[q][jj].x << 16); v[1] = __uint_as_float(w[q][jj].x & 0xffff0000u); v[2] = __uint_as_float(w[q][jj].y << 16); v[3] = __uint_as_float(w[q][jj].y & 0xffff0000u);
;                     orow[64 * jj] = v * rq * gg; } }
;         }
	v_pk_mul_f32 v[4:5], v[10:11], v[4:5] op_sel_hi:[0,1]
	v_pk_mul_f32 v[0:1], v[180:181], v[4:5]
	v_pk_mul_f32 v[2:3], v[182:183], v[6:7]
	global_store_dwordx4 v[8:9], v[0:3], off offset:1024
	v_lshlrev_b32_e32 v4, 16, v54
	v_and_b32_e32 v5, 0xffff0000, v54
	v_lshlrev_b32_e32 v6, 16, v55
	v_and_b32_e32 v7, 0xffff0000, v55
	v_pk_mul_f32 v[6:7], v[10:11], v[6:7] op_sel_hi:[0,1]
	v_pk_mul_f32 v[4:5], v[10:11], v[4:5] op_sel_hi:[0,1]
	v_pk_mul_f32 v[0:1], v[184:185], v[4:5]
	v_pk_mul_f32 v[2:3], v[186:187], v[6:7]
	global_store_dwordx4 v[8:9], v[0:3], off offset:2048
	v_lshlrev_b32_e32 v4, 16, v52
	v_and_b32_e32 v5, 0xffff0000, v52
	v_lshlrev_b32_e32 v6, 16, v53
	v_and_b32_e32 v7, 0xffff0000, v53
	v_pk_mul_f32 v[6:7], v[10:11], v[6:7] op_sel_hi:[0,1]
	v_pk_mul_f32 v[4:5], v[10:11], v[4:5] op_sel_hi:[0,1]
	v_pk_mul_f32 v[0:1], v[188:189], v[4:5]
	v_pk_mul_f32 v[2:3], v[190:191], v[6:7]
	global_store_dwordx4 v[8:9], v[0:3], off offset:3072
	v_lshlrev_b32_e32 v6, 16, v50
	v_and_b32_e32 v7, 0xffff0000, v50
	v_lshlrev_b32_e32 v8, 16, v51
	v_and_b32_e32 v9, 0xffff0000, v51
	v_add_co_u32_e32 v4, vcc, s27, v22
	v_pk_mul_f32 v[8:9], v[10:11], v[8:9] op_sel_hi:[0,1]
	v_pk_mul_f32 v[6:7], v[10:11], v[6:7] op_sel_hi:[0,1]
	v_addc_co_u32_e32 v5, vcc, 0, v23, vcc
	v_pk_mul_f32 v[0:1], v[192:193], v[6:7]
	v_pk_mul_f32 v[2:3], v[194:195], v[8:9]
	global_store_dwordx4 v[4:5], v[0:3], off offset:-4096
	v_lshlrev_b32_e32 v8, 16, v48
	v_and_b32_e32 v9, 0xffff0000, v48
	v_lshlrev_b32_e32 v48, 16, v49
	v_and_b32_e32 v49, 0xffff0000, v49
	v_add_co_u32_e32 v6, vcc, s26, v22
	v_pk_mul_f32 v[48:49], v[10:11], v[48:49] op_sel_hi:[0,1]
	v_pk_mul_f32 v[8:9], v[10:11], v[8:9] op_sel_hi:[0,1]
	v_addc_co_u32_e32 v7, vcc, 0, v23, vcc
	v_cmp_gt_f32_e32 vcc, s1, v11
	v_pk_mul_f32 v[0:1], v[196:197], v[8:9]
	v_pk_mul_f32 v[2:3], v[198:199], v[48:49]
	global_store_dwordx4 v[6:7], v[0:3], off offset:1024
	v_lshlrev_b32_e32 v8, 16, v46
	v_and_b32_e32 v9, 0xffff0000, v46
	v_lshlrev_b32_e32 v46, 16, v47
	v_and_b32_e32 v47, 0xffff0000, v47
	v_pk_mul_f32 v[46:47], v[10:11], v[46:47] op_sel_hi:[0,1]
	v_pk_mul_f32 v[8:9], v[10:11], v[8:9] op_sel_hi:[0,1]
	v_pk_mul_f32 v[0:1], v[200:201], v[8:9]
	v_pk_mul_f32 v[2:3], v[202:203], v[46:47]
	global_store_dwordx4 v[6:7], v[0:3], off offset:2048
	v_lshlrev_b32_e32 v8, 16, v44
	v_and_b32_e32 v9, 0xffff0000, v44
	v_lshlrev_b32_e32 v44, 16, v45
	v_and_b32_e32 v45, 0xffff0000, v45
	v_pk_mul_f32 v[44:45], v[10:11], v[44:45] op_sel_hi:[0,1]
	v_pk_mul_f32 v[8:9], v[10:11], v[8:9] op_sel_hi:[0,1]
	v_pk_mul_f32 v[0:1], v[204:205], v[8:9]
	v_pk_mul_f32 v[2:3], v[206:207], v[44:45]
	global_store_dwordx4 v[6:7], v[0:3], off offset:3072
	v_mul_f32_e32 v6, 0x4b800000, v11
	v_cndmask_b32_e32 v6, v11, v6, vcc
	v_rsq_f32_e32 v10, v6
	v_lshlrev_b32_e32 v6, 16, v42
	v_and_b32_e32 v7, 0xffff0000, v42
	v_lshlrev_b32_e32 v8, 16, v43
	v_mul_f32_e32 v11, 0x45800000, v10
	v_and_b32_e32 v9, 0xffff0000, v43
	v_cndmask_b32_e32 v10, v10, v11, vcc
	v_pk_mul_f32 v[8:9], v[10:11], v[8:9] op_sel_hi:[0,1]
	v_pk_mul_f32 v[6:7], v[10:11], v[6:7] op_sel_hi:[0,1]
	v_pk_mul_f32 v[0:1], v[176:177], v[6:7]
	v_pk_mul_f32 v[2:3], v[178:179], v[8:9]
	global_store_dwordx4 v[4:5], v[0:3], off
	v_lshlrev_b32_e32 v6, 16, v40
	v_and_b32_e32 v7, 0xffff0000, v40
	v_lshlrev_b32_e32 v8, 16, v41
	v_and_b32_e32 v9, 0xffff0000, v41
	v_pk_mul_f32 v[8:9], v[10:11], v[8:9] op_sel_hi:[0,1]
	v_pk_mul_f32 v[6:7], v[10:11], v[6:7] op_sel_hi:[0,1]
	v_pk_mul_f32 v[0:1], v[180:181], v[6:7]
	v_pk_mul_f32 v[2:3], v[182:183], v[8:9]
	global_store_dwordx4 v[4:5], v[0:3], off offset:1024
	v_lshlrev_b32_e32 v6, 16, v38
	v_and_b32_e32 v7, 0xffff0000, v38
	v_lshlrev_b32_e32 v8, 16, v39
	v_and_b32_e32 v9, 0xffff0000, v39
	v_pk_mul_f32 v[8:9], v[10:11], v[8:9] op_sel_hi:[0,1]
	v_pk_mul_f32 v[6:7], v[10:11], v[6:7] op_sel_hi:[0,1]
	v_pk_mul_f32 v[0:1], v[184:185], v[6:7]
	v_pk_mul_f32 v[2:3], v[186:187], v[8:9]
	global_store_dwordx4 v[4:5], v[0:3], off offset:2048
	v_lshlrev_b32_e32 v6, 16, v36
	v_and_b32_e32 v7, 0xffff0000, v36
	v_lshlrev_b32_e32 v8, 16, v37
	v_and_b32_e32 v9, 0xffff0000, v37
	v_pk_mul_f32 v[8:9], v[10:11], v[8:9] op_sel_hi:[0,1]
	v_pk_mul_f32 v[6:7], v[10:11], v[6:7] op_sel_hi:[0,1]
	v_pk_mul_f32 v[0:1], v[188:189], v[6:7]
	v_pk_mul_f32 v[2:3], v[190:191], v[8:9]
	global_store_dwordx4 v[4:5], v[0:3], off offset:3072
	v_lshlrev_b32_e32 v6, 16, v34
	v_and_b32_e32 v7, 0xffff0000, v34
	v_lshlrev_b32_e32 v8, 16, v35
	v_and_b32_e32 v9, 0xffff0000, v35
	v_add_co_u32_e32 v4, vcc, s28, v22
	v_pk_mul_f32 v[8:9], v[10:11], v[8:9] op_sel_hi:[0,1]
	v_pk_mul_f32 v[6:7], v[10:11], v[6:7] op_sel_hi:[0,1]
	v_addc_co_u32_e32 v5, vcc, 0, v23, vcc
	v_lshl_add_u64 v[22:23], v[22:23], 0, s[8:9]
	v_pk_mul_f32 v[0:1], v[192:193], v[6:7]
	v_pk_mul_f32 v[2:3], v[194:195], v[8:9]
	global_store_dwordx4 v[4:5], v[0:3], off
	v_lshlrev_b32_e32 v6, 16, v32
	v_and_b32_e32 v7, 0xffff0000, v32
	v_lshlrev_b32_e32 v8, 16, v33
	v_and_b32_e32 v9, 0xffff0000, v33
	v_pk_mul_f32 v[8:9], v[10:11], v[8:9] op_sel_hi:[0,1]
	v_pk_mul_f32 v[6:7], v[10:11], v[6:7] op_sel_hi:[0,1]
	v_pk_mul_f32 v[0:1], v[196:197], v[6:7]
	v_pk_mul_f32 v[2:3], v[198:199], v[8:9]
	global_store_dwordx4 v[4:5], v[0:3], off offset:1024
	v_lshlrev_b32_e32 v6, 16, v30
	v_and_b32_e32 v7, 0xffff0000, v30
	v_lshlrev_b32_e32 v8, 16, v31
	v_and_b32_e32 v9, 0xffff0000, v31
	v_pk_mul_f32 v[8:9], v[10:11], v[8:9] op_sel_hi:[0,1]
	v_pk_mul_f32 v[6:7], v[10:11], v[6:7] op_sel_hi:[0,1]
	v_pk_mul_f32 v[0:1], v[200:201], v[6:7]
	v_pk_mul_f32 v[2:3], v[202:203], v[8:9]
	global_store_dwordx4 v[4:5], v[0:3], off offset:2048
	v_lshlrev_b32_e32 v6, 16, v28
	v_and_b32_e32 v7, 0xffff0000, v28
	v_lshlrev_b32_e32 v8, 16, v29
	v_and_b32_e32 v9, 0xffff0000, v29
	v_pk_mul_f32 v[8:9], v[10:11], v[8:9] op_sel_hi:[0,1]
	v_pk_mul_f32 v[6:7], v[10:11], v[6:7] op_sel_hi:[0,1]
	v_pk_mul_f32 v[0:1], v[204:205], v[6:7]
	v_pk_mul_f32 v[2:3], v[206:207], v[8:9]
	global_store_dwordx4 v[4:5], v[0:3], off offset:3072
	s_cbranch_scc0 .LBB0_906
